# mLSTM chunk kernel: 16 exec-masked ds_read+wait blocks for the causal decay weights replaced by 4 ds_read_b128 + branch-free compare/select; in-proj GEMM start stagger in 4 groups (0/6/12/18 us)
# speedup vs baseline: 1.0281x; 1.0091x over previous
.LBB0_260:
	s_cmp_lt_u32 s74, 32
	s_cbranch_scc1 .Lmy_nodelay_end
	s_bitcmp1_b32 s74, 3
	s_cbranch_scc0 .Lmy_nodelay_0
	s_sleep 64
	s_sleep 64
	s_sleep 64
.Lmy_nodelay_0:
	s_bitcmp1_b32 s74, 4
	s_cbranch_scc0 .Lmy_nodelay_1
	s_sleep 64
	s_sleep 64
	s_sleep 64
	s_sleep 64
	s_sleep 64
	s_sleep 64
.Lmy_nodelay_1:
.Lmy_nodelay_end:
	s_cmp_lt_i32 s86, 3
	s_cselect_b64 s[8:9], -1, 0
	s_and_b64 s[0:1], s[8:9], s[0:1]
	v_writelane_b32 v253, s78, 57
	s_andn2_b64 vcc, exec, s[0:1]
	s_nop 0
	v_writelane_b32 v253, s79, 58
	s_cbranch_vccnz .LBB0_672
	s_abs_i32 s0, s78
	v_cvt_f32_u32_e32 v1, s0
	s_sub_i32 s2, 0, s0
	s_mov_b32 s1, s74
	v_rcp_iflag_f32_e32 v1, v1
	s_barrier
	v_mul_f32_e32 v1, 0x4f7ffffe, v1
	v_cvt_u32_f32_e32 v1, v1
	s_ashr_i32 s3, s1, 31
	s_abs_i32 s1, s1
	v_mov_b32_e32 v10, v202
	v_readfirstlane_b32 s4, v1
	s_mul_i32 s2, s2, s4
	s_mul_hi_u32 s2, s4, s2
	s_add_i32 s4, s4, s2
	s_mul_hi_u32 s2, s1, s4
	s_mul_i32 s2, s2, s0
	s_sub_i32 s1, s1, s2
	s_sub_i32 s2, s1, s0
	s_cmp_ge_u32 s1, s0
	s_cselect_b32 s1, s2, s1
	s_sub_i32 s2, s1, s0
	s_cmp_ge_u32 s1, s0
	s_cselect_b32 s0, s2, s1
	s_xor_b32 s0, s0, s3
	s_sub_i32 s24, s0, s3
	s_cmpk_lt_i32 s24, 0x720
	s_cselect_b64 s[0:1], -1, 0
	s_cmpk_gt_i32 s24, 0x71f
	v_readfirstlane_b32 s20, v10
	s_cbranch_scc1 .LBB0_263
	s_ashr_i32 s2, s24, 31
	s_lshr_b32 s2, s2, 29
	s_add_i32 s2, s24, s2
	s_ashr_i32 s3, s2, 3
	s_and_b32 s2, s2, -8
	s_sub_i32 s2, s24, s2
	s_cmp_lt_i32 s2, 0
	s_movk_i32 s4, 0xe5
	s_cselect_b32 s4, s4, 0xe4
	s_mul_i32 s2, s2, s4
	s_add_i32 s2, s2, s3
	s_mul_hi_i32 s3, s2, 0x6bca1af3
	s_lshr_b32 s4, s3, 31
	s_ashr_i32 s3, s3, 6
	s_add_i32 s3, s3, s4
	s_lshl_b32 s4, s3, 3
	s_mulk_i32 s3, 0x98
	s_sub_i32 s2, s2, s3
	s_bfe_u32 s3, s2, 0x3001c
	s_add_i32 s3, s2, s3
	s_sext_i32_i16 s5, s3
	s_and_b32 s3, s3, 0xfff8
	s_sub_i32 s2, s2, s3
	s_sext_i32_i16 s2, s2
	s_add_i32 s2, s4, s2
	s_ashr_i32 s10, s5, 3

.LBB0_986:
	v_add_u32_e32 v224, 0, v153
	ds_read_b128 v[66:69], v224
	ds_read_b128 v[70:73], v201
	ds_read_b128 v[208:211], v201 offset:32
	ds_read_b128 v[212:215], v224 offset:32
	s_waitcnt lgkmcnt(2)
	v_mfma_f32_32x32x16_bf16 v[66:81], v[66:69], v[70:73], 0
	s_waitcnt lgkmcnt(0)
	v_mfma_f32_32x32x16_bf16 v[66:81], v[212:215], v[208:211], v[66:81]
	ds_read_b128 v[208:211], v224 offset:64
	ds_read_b128 v[212:215], v201 offset:64
	ds_read_b128 v[216:219], v201 offset:96
	ds_read_b128 v[220:223], v224 offset:96
	s_waitcnt lgkmcnt(2)
	v_mfma_f32_32x32x16_bf16 v[66:81], v[208:211], v[212:215], v[66:81]
	s_waitcnt lgkmcnt(0)
	v_mfma_f32_32x32x16_bf16 v[66:81], v[220:223], v[216:219], v[66:81]
	ds_read_b128 v[208:211], v224 offset:128
	ds_read_b128 v[212:215], v201 offset:128
	ds_read_b128 v[216:219], v201 offset:160
	ds_read_b128 v[220:223], v224 offset:160
	s_waitcnt lgkmcnt(2)
	v_mfma_f32_32x32x16_bf16 v[66:81], v[208:211], v[212:215], v[66:81]
	s_waitcnt lgkmcnt(0)
	v_mfma_f32_32x32x16_bf16 v[66:81], v[220:223], v[216:219], v[66:81]
	ds_read_b128 v[208:211], v224 offset:192
	ds_read_b128 v[212:215], v201 offset:192
	ds_read_b128 v[216:219], v201 offset:224
	ds_read_b128 v[220:223], v224 offset:224
	s_waitcnt lgkmcnt(2)
	v_mfma_f32_32x32x16_bf16 v[66:81], v[208:211], v[212:215], v[66:81]
	s_waitcnt lgkmcnt(0)
	v_mfma_f32_32x32x16_bf16 v[66:81], v[220:223], v[216:219], v[66:81]
	v_add_u32_e32 v252, 0x12800, v149
	ds_read_b128 v[242:245], v252 offset:0
	ds_read_b128 v[246:249], v252 offset:32
	v_subrev_u32_e32 v250, 27, v151
	v_sub_u32_e32 v250, v172, v250
	v_add_u32_e32 v251, -1, v250
	v_cndmask_b32_e64 v250, v251, v250, s[16:17]
	v_mov_b32_e32 v251, 0
	s_waitcnt lgkmcnt(0)
	v_sub_f32_e32 v242, v242, v204
	v_mul_f32_e32 v242, 0x3fb8aa3b, v242
	v_exp_f32_e32 v242, v242
	v_sub_f32_e32 v243, v243, v204
	v_mul_f32_e32 v243, 0x3fb8aa3b, v243
	v_exp_f32_e32 v243, v243
	v_sub_f32_e32 v244, v244, v204
	v_mul_f32_e32 v244, 0x3fb8aa3b, v244
	v_exp_f32_e32 v244, v244
	v_sub_f32_e32 v245, v245, v204
	v_mul_f32_e32 v245, 0x3fb8aa3b, v245
	v_exp_f32_e32 v245, v245
	v_sub_f32_e32 v246, v246, v204
	v_mul_f32_e32 v246, 0x3fb8aa3b, v246
	v_exp_f32_e32 v246, v246
	v_sub_f32_e32 v247, v247, v204
	v_mul_f32_e32 v247, 0x3fb8aa3b, v247
	v_exp_f32_e32 v247, v247
	v_sub_f32_e32 v248, v248, v204
	v_mul_f32_e32 v248, 0x3fb8aa3b, v248
	v_exp_f32_e32 v248, v248
	v_sub_f32_e32 v249, v249, v204
	v_mul_f32_e32 v249, 0x3fb8aa3b, v249
	v_exp_f32_e32 v249, v249
	v_cmp_le_i32_e64 s[20:21], 0, v250
	s_xor_b64 s[20:21], s[20:21], s[16:17]
	v_cndmask_b32_e64 v209, v242, v251, s[20:21]
	v_cmp_le_i32_e64 s[20:21], 1, v250
	s_xor_b64 s[20:21], s[20:21], s[16:17]
	v_cndmask_b32_e64 v210, v243, v251, s[20:21]
	v_cmp_le_i32_e64 s[20:21], 2, v250
	s_xor_b64 s[20:21], s[20:21], s[16:17]
	v_cndmask_b32_e64 v208, v244, v251, s[20:21]
	v_cmp_le_i32_e64 s[20:21], 3, v250
	s_xor_b64 s[20:21], s[20:21], s[16:17]
	v_cndmask_b32_e64 v212, v245, v251, s[20:21]
	v_cmp_le_i32_e64 s[20:21], 8, v250
	s_xor_b64 s[20:21], s[20:21], s[16:17]
	v_cndmask_b32_e64 v211, v246, v251, s[20:21]
	v_cmp_le_i32_e64 s[20:21], 9, v250
	s_xor_b64 s[20:21], s[20:21], s[16:17]
	v_cndmask_b32_e64 v214, v247, v251, s[20:21]
	v_cmp_le_i32_e64 s[20:21], 10, v250
	s_xor_b64 s[20:21], s[20:21], s[16:17]
	v_cndmask_b32_e64 v213, v248, v251, s[20:21]
	v_cmp_le_i32_e64 s[20:21], 11, v250
	s_xor_b64 s[20:21], s[20:21], s[16:17]
	v_cndmask_b32_e64 v218, v249, v251, s[20:21]
	ds_read_b128 v[242:245], v252 offset:64
	ds_read_b128 v[246:249], v252 offset:96
	s_waitcnt lgkmcnt(0)
	v_sub_f32_e32 v242, v242, v204
	v_mul_f32_e32 v242, 0x3fb8aa3b, v242
	v_exp_f32_e32 v242, v242
	v_sub_f32_e32 v243, v243, v204
	v_mul_f32_e32 v243, 0x3fb8aa3b, v243
	v_exp_f32_e32 v243, v243
	v_sub_f32_e32 v244, v244, v204
	v_mul_f32_e32 v244, 0x3fb8aa3b, v244
	v_exp_f32_e32 v244, v244
	v_sub_f32_e32 v245, v245, v204
	v_mul_f32_e32 v245, 0x3fb8aa3b, v245
	v_exp_f32_e32 v245, v245
	v_sub_f32_e32 v246, v246, v204
	v_mul_f32_e32 v246, 0x3fb8aa3b, v246
	v_exp_f32_e32 v246, v246
	v_sub_f32_e32 v247, v247, v204
	v_mul_f32_e32 v247, 0x3fb8aa3b, v247
	v_exp_f32_e32 v247, v247
	v_sub_f32_e32 v248, v248, v204
	v_mul_f32_e32 v248, 0x3fb8aa3b, v248
	v_exp_f32_e32 v248, v248
	v_sub_f32_e32 v249, v249, v204
	v_mul_f32_e32 v249, 0x3fb8aa3b, v249
	v_exp_f32_e32 v249, v249
	v_cmp_le_i32_e64 s[20:21], 16, v250
	s_xor_b64 s[20:21], s[20:21], s[16:17]
	v_cndmask_b32_e64 v217, v242, v251, s[20:21]
	v_cmp_le_i32_e64 s[20:21], 17, v250
	s_xor_b64 s[20:21], s[20:21], s[16:17]
	v_cndmask_b32_e64 v216, v243, v251, s[20:21]
	v_cmp_le_i32_e64 s[20:21], 18, v250
	s_xor_b64 s[20:21], s[20:21], s[16:17]
	v_cndmask_b32_e64 v215, v244, v251, s[20:21]
	v_cmp_le_i32_e64 s[20:21], 19, v250
	s_xor_b64 s[20:21], s[20:21], s[16:17]
	v_cndmask_b32_e64 v220, v245, v251, s[20:21]
	v_cmp_le_i32_e64 s[20:21], 24, v250
	s_xor_b64 s[20:21], s[20:21], s[16:17]
	v_cndmask_b32_e64 v219, v246, v251, s[20:21]
	v_cmp_le_i32_e64 s[20:21], 25, v250
	s_xor_b64 s[20:21], s[20:21], s[16:17]
	v_cndmask_b32_e64 v223, v247, v251, s[20:21]
	v_cmp_le_i32_e64 s[20:21], 26, v250
	s_xor_b64 s[20:21], s[20:21], s[16:17]
	v_cndmask_b32_e64 v222, v248, v251, s[20:21]
	v_cmp_le_i32_e64 s[20:21], 27, v250
	s_xor_b64 s[20:21], s[20:21], s[16:17]
	v_cndmask_b32_e64 v224, v249, v251, s[20:21]
	s_mov_b64 s[60:61], 0
	s_branch .LBB0_985

.LBB0_1145:
	v_add_u32_e32 v224, 0, v153
	ds_read_b128 v[66:69], v224
	ds_read_b128 v[70:73], v201
	ds_read_b128 v[208:211], v201 offset:32
	ds_read_b128 v[212:215], v224 offset:32
	s_waitcnt lgkmcnt(2)
	v_mfma_f32_32x32x16_bf16 v[66:81], v[66:69], v[70:73], 0
	s_waitcnt lgkmcnt(0)
	v_mfma_f32_32x32x16_bf16 v[66:81], v[212:215], v[208:211], v[66:81]
	ds_read_b128 v[208:211], v224 offset:64
	ds_read_b128 v[212:215], v201 offset:64
	ds_read_b128 v[216:219], v201 offset:96
	ds_read_b128 v[220:223], v224 offset:96
	s_waitcnt lgkmcnt(2)
	v_mfma_f32_32x32x16_bf16 v[66:81], v[208:211], v[212:215], v[66:81]
	s_waitcnt lgkmcnt(0)
	v_mfma_f32_32x32x16_bf16 v[66:81], v[220:223], v[216:219], v[66:81]
	ds_read_b128 v[208:211], v224 offset:128
	ds_read_b128 v[212:215], v201 offset:128
	ds_read_b128 v[216:219], v201 offset:160
	ds_read_b128 v[220:223], v224 offset:160
	s_waitcnt lgkmcnt(2)
	v_mfma_f32_32x32x16_bf16 v[66:81], v[208:211], v[212:215], v[66:81]
	s_waitcnt lgkmcnt(0)
	v_mfma_f32_32x32x16_bf16 v[66:81], v[220:223], v[216:219], v[66:81]
	ds_read_b128 v[208:211], v224 offset:192
	ds_read_b128 v[212:215], v201 offset:192
	ds_read_b128 v[216:219], v201 offset:224
	ds_read_b128 v[220:223], v224 offset:224
	s_waitcnt lgkmcnt(2)
	v_mfma_f32_32x32x16_bf16 v[66:81], v[208:211], v[212:215], v[66:81]
	s_waitcnt lgkmcnt(0)
	v_mfma_f32_32x32x16_bf16 v[66:81], v[220:223], v[216:219], v[66:81]
	v_add_u32_e32 v252, 0x12800, v149
	ds_read_b128 v[242:245], v252 offset:0
	ds_read_b128 v[246:249], v252 offset:32
	v_subrev_u32_e32 v250, 27, v151
	v_sub_u32_e32 v250, v171, v250
	v_add_u32_e32 v251, -1, v250
	v_cndmask_b32_e64 v250, v251, v250, s[16:17]
	v_mov_b32_e32 v251, 0
	s_waitcnt lgkmcnt(0)
	v_sub_f32_e32 v242, v242, v204
	v_mul_f32_e32 v242, 0x3fb8aa3b, v242
	v_exp_f32_e32 v242, v242
	v_sub_f32_e32 v243, v243, v204
	v_mul_f32_e32 v243, 0x3fb8aa3b, v243
	v_exp_f32_e32 v243, v243
	v_sub_f32_e32 v244, v244, v204
	v_mul_f32_e32 v244, 0x3fb8aa3b, v244
	v_exp_f32_e32 v244, v244
	v_sub_f32_e32 v245, v245, v204
	v_mul_f32_e32 v245, 0x3fb8aa3b, v245
	v_exp_f32_e32 v245, v245
	v_sub_f32_e32 v246, v246, v204
	v_mul_f32_e32 v246, 0x3fb8aa3b, v246
	v_exp_f32_e32 v246, v246
	v_sub_f32_e32 v247, v247, v204
	v_mul_f32_e32 v247, 0x3fb8aa3b, v247
	v_exp_f32_e32 v247, v247
	v_sub_f32_e32 v248, v248, v204
	v_mul_f32_e32 v248, 0x3fb8aa3b, v248
	v_exp_f32_e32 v248, v248
	v_sub_f32_e32 v249, v249, v204
	v_mul_f32_e32 v249, 0x3fb8aa3b, v249
	v_exp_f32_e32 v249, v249
	v_cmp_le_i32_e32 vcc, 0, v250
	s_xor_b64 vcc, vcc, s[16:17]
	v_cndmask_b32_e32 v209, v242, v251, vcc
	v_cmp_le_i32_e32 vcc, 1, v250
	s_xor_b64 vcc, vcc, s[16:17]
	v_cndmask_b32_e32 v210, v243, v251, vcc
	v_cmp_le_i32_e32 vcc, 2, v250
	s_xor_b64 vcc, vcc, s[16:17]
	v_cndmask_b32_e32 v208, v244, v251, vcc
	v_cmp_le_i32_e32 vcc, 3, v250
	s_xor_b64 vcc, vcc, s[16:17]
	v_cndmask_b32_e32 v212, v245, v251, vcc
	v_cmp_le_i32_e32 vcc, 8, v250
	s_xor_b64 vcc, vcc, s[16:17]
	v_cndmask_b32_e32 v211, v246, v251, vcc
	v_cmp_le_i32_e32 vcc, 9, v250
	s_xor_b64 vcc, vcc, s[16:17]
	v_cndmask_b32_e32 v214, v247, v251, vcc
	v_cmp_le_i32_e32 vcc, 10, v250
	s_xor_b64 vcc, vcc, s[16:17]
	v_cndmask_b32_e32 v213, v248, v251, vcc
	v_cmp_le_i32_e32 vcc, 11, v250
	s_xor_b64 vcc, vcc, s[16:17]
	v_cndmask_b32_e32 v218, v249, v251, vcc
	ds_read_b128 v[242:245], v252 offset:64
	ds_read_b128 v[246:249], v252 offset:96
	s_waitcnt lgkmcnt(0)
	v_sub_f32_e32 v242, v242, v204
	v_mul_f32_e32 v242, 0x3fb8aa3b, v242
	v_exp_f32_e32 v242, v242
	v_sub_f32_e32 v243, v243, v204
	v_mul_f32_e32 v243, 0x3fb8aa3b, v243
	v_exp_f32_e32 v243, v243
	v_sub_f32_e32 v244, v244, v204
	v_mul_f32_e32 v244, 0x3fb8aa3b, v244
	v_exp_f32_e32 v244, v244
	v_sub_f32_e32 v245, v245, v204
	v_mul_f32_e32 v245, 0x3fb8aa3b, v245
	v_exp_f32_e32 v245, v245
	v_sub_f32_e32 v246, v246, v204
	v_mul_f32_e32 v246, 0x3fb8aa3b, v246
	v_exp_f32_e32 v246, v246
	v_sub_f32_e32 v247, v247, v204
	v_mul_f32_e32 v247, 0x3fb8aa3b, v247
	v_exp_f32_e32 v247, v247
	v_sub_f32_e32 v248, v248, v204
	v_mul_f32_e32 v248, 0x3fb8aa3b, v248
	v_exp_f32_e32 v248, v248
	v_sub_f32_e32 v249, v249, v204
	v_mul_f32_e32 v249, 0x3fb8aa3b, v249
	v_exp_f32_e32 v249, v249
	v_cmp_le_i32_e32 vcc, 16, v250
	s_xor_b64 vcc, vcc, s[16:17]
	v_cndmask_b32_e32 v217, v242, v251, vcc
	v_cmp_le_i32_e32 vcc, 17, v250
	s_xor_b64 vcc, vcc, s[16:17]
	v_cndmask_b32_e32 v216, v243, v251, vcc
	v_cmp_le_i32_e32 vcc, 18, v250
	s_xor_b64 vcc, vcc, s[16:17]
	v_cndmask_b32_e32 v215, v244, v251, vcc
	v_cmp_le_i32_e32 vcc, 19, v250
	s_xor_b64 vcc, vcc, s[16:17]
	v_cndmask_b32_e32 v220, v245, v251, vcc
	v_cmp_le_i32_e32 vcc, 24, v250
	s_xor_b64 vcc, vcc, s[16:17]
	v_cndmask_b32_e32 v219, v246, v251, vcc
	v_cmp_le_i32_e32 vcc, 25, v250
	s_xor_b64 vcc, vcc, s[16:17]
	v_cndmask_b32_e32 v223, v247, v251, vcc
	v_cmp_le_i32_e32 vcc, 26, v250
	s_xor_b64 vcc, vcc, s[16:17]
	v_cndmask_b32_e32 v222, v248, v251, vcc
	v_cmp_le_i32_e32 vcc, 27, v250
	s_xor_b64 vcc, vcc, s[16:17]
	v_cndmask_b32_e32 v224, v249, v251, vcc
	s_mov_b64 s[58:59], 0
	s_branch .LBB0_1144
